# K-loops: 4th-segment LDS-DMA addresses via offset:128 on the 2nd-segment address registers (M0 -128) instead of six 64-bit adds; 2nd-segment address adds issued inside the preceding MFMA burst
# baseline (speedup 1.0000x reference)
; #define PG8_STAGE(bufoff, gbase, voff) do { _Pragma("unroll") for (int _i = 0; _i < 2; ++_i) \
;         __builtin_amdgcn_global_load_lds((const unsigned*)((const char*)(gbase) + (voff)[_i]), (LAS unsigned*)(lds + (bufoff) + ldsw + _i * 8192), 16, 0, 0); } while (0)
; #define PG8_LDA(dst, b, h) do { _Pragma("unroll") for (int m = 0; m < 4; ++m) _Pragma("unroll") for (int k = 0; k < 2; ++k) dst[m][k] = *(const LAS bf16x8*)(lds + PG8_SA(b, h) + aoff + m * 2048 + k * 1024); } while (0)
; #define PG8_LDB(dst, b, h) do { _Pragma("unroll") for (int n = 0; n < 2; ++n) _Pragma("unroll") for (int k = 0; k < 2; ++k) dst[n][k] = *(const LAS bf16x8*)(lds + PG8_SB(b, h) + boff + n * 2048 + k * 1024); } while (0)
; #define PG8_MMA(ai, bj, At, Bt) do { __builtin_amdgcn_s_setprio(1); _Pragma("unroll") for (int m = 0; m < 4; ++m) _Pragma("unroll") for (int n = 0; n < 2; ++n) _Pragma("unroll") for (int k = 0; k < 2; ++k) \
;         acc[ai][bj][m][n] = __builtin_amdgcn_mfma_f32_16x16x32_bf16(Bt[n][k], At[m][k], acc[ai][bj][m][n], 0, 0, 0); __builtin_amdgcn_s_setprio(0); } while (0)
; #define PG8_WAIT_V(n) asm volatile("s_waitcnt vmcnt(" #n ")" ::: "memory")
; #define PG8_WAIT_L(n) asm volatile("s_waitcnt lgkmcnt(" #n ")" ::: "memory")
; #define PG8_BAR __builtin_amdgcn_s_barrier()
; #define PG8_SCHED __builtin_amdgcn_sched_barrier(0)
;     ...
;         for (int t = 0; t < nt; t += 2) {
;             const bool last = (t == nt - 2);
;             const char* a1 = cA + (size_t)(t + 1) * kstep;
;             const char* a2 = last ? nA : cA + (size_t)(t + 2) * kstep; const char* b2 = last ? nB : cB + (size_t)(t + 2) * kstep;
;             const char* a3 = a2 + kstep; const char* b3 = b2 + kstep;
;             PG8_LDB(B0, 0, 0); PG8_LDB(B1, 0, 1); PG8_SCHED; PG8_LDA(At, 0, 0); PG8_STAGE(PG8_SA(1, 1), a1 + hstepA, voffA);
;             PG8_WAIT_V(8); PG8_WAIT_L(0); PG8_BAR; PG8_MMA(0, 0, At, B0); PG8_MMA(0, 1, At, B1); PG8_BAR; PG8_SCHED;
;             PG8_LDA(At, 0, 1); PG8_STAGE(PG8_SB(0, 0), b2, voffB); PG8_STAGE(PG8_SB(0, 1), b2 + hstepB, voffB); PG8_STAGE(PG8_SA(0, 0), a2, voffA);
;             PG8_WAIT_V(8); PG8_WAIT_L(0); PG8_BAR; PG8_MMA(1, 0, At, B0); PG8_MMA(1, 1, At, B1); PG8_BAR; PG8_SCHED;
.LBB0_159:
	s_add_i32 s38, s8, 2
	s_add_u32 s26, s12, s0
	s_addc_u32 s9, s13, s1
	s_add_i32 s27, 0, 0x10000
	s_cmp_eq_u32 s63, s8
	s_cselect_b32 s9, s18, s9
	s_cselect_b32 s8, s19, s26
	s_cselect_b64 vcc, -1, 0
	s_add_i32 s26, 0, 0x14000
	v_lshl_add_u64 v[150:151], v[188:189], 0, s[0:1]
	v_add_u32_e32 v146, s27, v226
	v_add_u32_e32 v162, s26, v226
	ds_read_b128 v[134:137], v146
	ds_read_b128 v[138:141], v146 offset:1024
	ds_read_b128 v[142:145], v146 offset:2048
	ds_read_b128 v[146:149], v146 offset:3072
	v_cndmask_b32_e32 v205, v151, v132, vcc
	v_cndmask_b32_e32 v204, v150, v133, vcc
	ds_read_b128 v[150:153], v162
	ds_read_b128 v[154:157], v162 offset:1024
	ds_read_b128 v[158:161], v162 offset:2048
	ds_read_b128 v[162:165], v162 offset:3072
	v_lshl_add_u64 v[212:213], s[12:13], 0, v[130:131]
	s_add_i32 m0, s20, 0xc000
	ds_read_b128 v[166:169], v227
	ds_read_b128 v[170:173], v227 offset:1024
	ds_read_b128 v[174:177], v227 offset:2048
	ds_read_b128 v[178:181], v227 offset:3072
	ds_read_b128 v[230:233], v227 offset:4096
	ds_read_b128 v[234:237], v227 offset:5120
	ds_read_b128 v[238:241], v227 offset:6144
	ds_read_b128 v[242:245], v227 offset:7168
	global_load_lds_dwordx4 v[212:213], off
	v_lshl_add_u64 v[212:213], s[12:13], 0, v[128:129]
	s_add_i32 m0, s20, 0xe000
	s_nop 0
	global_load_lds_dwordx4 v[212:213], off
	s_waitcnt vmcnt(8)
	s_waitcnt lgkmcnt(0)
	s_barrier
	s_setprio 1
	s_waitcnt lgkmcnt(0)
	v_mfma_f32_16x16x32_bf16 v[124:127], v[134:137], v[166:169], v[124:127]
	v_mfma_f32_16x16x32_bf16 v[0:3], v[142:145], v[166:169], v[0:3]
	v_mfma_f32_16x16x32_bf16 v[120:123], v[134:137], v[174:177], v[120:123]
	v_mfma_f32_16x16x32_bf16 v[116:119], v[142:145], v[174:177], v[116:119]
	v_mfma_f32_16x16x32_bf16 v[112:115], v[134:137], v[230:233], v[112:115]
	v_mfma_f32_16x16x32_bf16 v[108:111], v[142:145], v[230:233], v[108:111]
	v_lshl_add_u64 v[212:213], v[204:205], 0, v[192:193]
	v_mfma_f32_16x16x32_bf16 v[104:107], v[134:137], v[238:241], v[104:107]
	v_mfma_f32_16x16x32_bf16 v[4:7], v[142:145], v[238:241], v[4:7]
	v_lshl_add_u64 v[218:219], v[204:205], 0, v[196:197]
	v_mfma_f32_16x16x32_bf16 v[124:127], v[138:141], v[170:173], v[124:127]
	v_mfma_f32_16x16x32_bf16 v[0:3], v[146:149], v[170:173], v[0:3]
	v_lshl_add_u64 v[204:205], v[204:205], 0, v[198:199]
	v_mfma_f32_16x16x32_bf16 v[120:123], v[138:141], v[178:181], v[120:123]
	v_mfma_f32_16x16x32_bf16 v[116:119], v[146:149], v[178:181], v[116:119]
	v_lshl_add_u64 v[246:247], v[204:205], 0, v[192:193]
	v_mfma_f32_16x16x32_bf16 v[112:115], v[138:141], v[234:237], v[112:115]
	v_mfma_f32_16x16x32_bf16 v[108:111], v[146:149], v[234:237], v[108:111]
	v_lshl_add_u64 v[204:205], v[204:205], 0, v[196:197]
	v_mfma_f32_16x16x32_bf16 v[104:107], v[138:141], v[242:245], v[104:107]
	v_mfma_f32_16x16x32_bf16 v[4:7], v[146:149], v[242:245], v[4:7]
	v_lshl_add_u64 v[248:249], s[8:9], 0, v[190:191]
	v_mfma_f32_16x16x32_bf16 v[100:103], v[150:153], v[166:169], v[100:103]
	v_mfma_f32_16x16x32_bf16 v[96:99], v[158:161], v[166:169], v[96:99]
	v_lshl_add_u64 v[250:251], s[8:9], 0, v[194:195]
	v_mfma_f32_16x16x32_bf16 v[92:95], v[150:153], v[174:177], v[92:95]
	v_mfma_f32_16x16x32_bf16 v[88:91], v[158:161], v[174:177], v[88:91]
	v_mfma_f32_16x16x32_bf16 v[84:87], v[150:153], v[230:233], v[84:87]
	v_mfma_f32_16x16x32_bf16 v[80:83], v[158:161], v[230:233], v[80:83]
	v_mfma_f32_16x16x32_bf16 v[76:79], v[150:153], v[238:241], v[76:79]
	v_mfma_f32_16x16x32_bf16 v[72:75], v[158:161], v[238:241], v[72:75]
	v_mfma_f32_16x16x32_bf16 v[100:103], v[154:157], v[170:173], v[100:103]
	v_mfma_f32_16x16x32_bf16 v[96:99], v[162:165], v[170:173], v[96:99]
	v_mfma_f32_16x16x32_bf16 v[92:95], v[154:157], v[178:181], v[92:95]
	v_mfma_f32_16x16x32_bf16 v[88:91], v[162:165], v[178:181], v[88:91]
	v_mfma_f32_16x16x32_bf16 v[84:87], v[154:157], v[234:237], v[84:87]
	v_mfma_f32_16x16x32_bf16 v[80:83], v[162:165], v[234:237], v[80:83]
	v_mfma_f32_16x16x32_bf16 v[76:79], v[154:157], v[242:245], v[76:79]
	v_mfma_f32_16x16x32_bf16 v[72:75], v[162:165], v[242:245], v[72:75]
	s_setprio 0
	s_barrier
	s_add_i32 s27, s27, s11
	s_mov_b32 m0, s27
	ds_read_b128 v[166:169], v227 offset:16384
	ds_read_b128 v[170:173], v227 offset:17408
	ds_read_b128 v[174:177], v227 offset:18432
	ds_read_b128 v[178:181], v227 offset:19456
	ds_read_b128 v[230:233], v227 offset:20480
	ds_read_b128 v[234:237], v227 offset:21504
	ds_read_b128 v[238:241], v227 offset:22528
	ds_read_b128 v[242:245], v227 offset:23552
	global_load_lds_dwordx4 v[212:213], off
	s_add_i32 m0, s27, 0x2000
	s_add_i32 s26, s26, s11
	global_load_lds_dwordx4 v[218:219], off
	s_mov_b32 m0, s26
	s_nop 0
	global_load_lds_dwordx4 v[246:247], off
	s_add_i32 m0, s26, 0x2000
	s_nop 0
	global_load_lds_dwordx4 v[204:205], off
	s_mov_b32 m0, s20
	s_nop 0
	global_load_lds_dwordx4 v[248:249], off
	s_mov_b32 m0, s48
	s_nop 0
	global_load_lds_dwordx4 v[250:251], off
	s_waitcnt vmcnt(8)
	s_waitcnt lgkmcnt(0)
	s_barrier
; #define PG8_STAGE(bufoff, gbase, voff) do { _Pragma("unroll") for (int _i = 0; _i < 2; ++_i) \
;         __builtin_amdgcn_global_load_lds((const unsigned*)((const char*)(gbase) + (voff)[_i]), (LAS unsigned*)(lds + (bufoff) + ldsw + _i * 8192), 16, 0, 0); } while (0)
; #define PG8_LDA(dst, b, h) do { _Pragma("unroll") for (int m = 0; m < 4; ++m) _Pragma("unroll") for (int k = 0; k < 2; ++k) dst[m][k] = *(const LAS bf16x8*)(lds + PG8_SA(b, h) + aoff + m * 2048 + k * 1024); } while (0)
; #define PG8_LDB(dst, b, h) do { _Pragma("unroll") for (int n = 0; n < 2; ++n) _Pragma("unroll") for (int k = 0; k < 2; ++k) dst[n][k] = *(const LAS bf16x8*)(lds + PG8_SB(b, h) + boff + n * 2048 + k * 1024); } while (0)
; #define PG8_MMA(ai, bj, At, Bt) do { __builtin_amdgcn_s_setprio(1); _Pragma("unroll") for (int m = 0; m < 4; ++m) _Pragma("unroll") for (int n = 0; n < 2; ++n) _Pragma("unroll") for (int k = 0; k < 2; ++k) \
;         acc[ai][bj][m][n] = __builtin_amdgcn_mfma_f32_16x16x32_bf16(Bt[n][k], At[m][k], acc[ai][bj][m][n], 0, 0, 0); __builtin_amdgcn_s_setprio(0); } while (0)
; #define PG8_WAIT_V(n) asm volatile("s_waitcnt vmcnt(" #n ")" ::: "memory")
; #define PG8_WAIT_L(n) asm volatile("s_waitcnt lgkmcnt(" #n ")" ::: "memory")
; #define PG8_BAR __builtin_amdgcn_s_barrier()
; #define PG8_SCHED __builtin_amdgcn_sched_barrier(0)
;     ...
;             PG8_WAIT_V(8); PG8_WAIT_L(0); PG8_BAR; PG8_MMA(1, 0, At, B0); PG8_MMA(1, 1, At, B1); PG8_BAR; PG8_SCHED;
;             PG8_LDB(B0, 1, 0); PG8_LDB(B1, 1, 1); PG8_SCHED; PG8_LDA(At, 1, 0); PG8_STAGE(PG8_SA(0, 1), a2 + hstepA, voffA);
;             PG8_WAIT_V(8); PG8_WAIT_L(0); PG8_BAR; PG8_MMA(0, 0, At, B0); PG8_MMA(0, 1, At, B1); PG8_BAR; PG8_SCHED;
	s_setprio 1
	s_waitcnt lgkmcnt(0)
	v_mfma_f32_16x16x32_bf16 v[68:71], v[134:137], v[166:169], v[68:71]
	v_mfma_f32_16x16x32_bf16 v[8:11], v[142:145], v[166:169], v[8:11]
	v_mfma_f32_16x16x32_bf16 v[64:67], v[134:137], v[174:177], v[64:67]
	v_mfma_f32_16x16x32_bf16 v[60:63], v[142:145], v[174:177], v[60:63]
	v_mfma_f32_16x16x32_bf16 v[56:59], v[134:137], v[230:233], v[56:59]
	v_mfma_f32_16x16x32_bf16 v[52:55], v[142:145], v[230:233], v[52:55]
	v_mfma_f32_16x16x32_bf16 v[48:51], v[134:137], v[238:241], v[48:51]
	v_mfma_f32_16x16x32_bf16 v[12:15], v[142:145], v[238:241], v[12:15]
	v_mfma_f32_16x16x32_bf16 v[68:71], v[138:141], v[170:173], v[68:71]
	v_mfma_f32_16x16x32_bf16 v[8:11], v[146:149], v[170:173], v[8:11]
	v_mfma_f32_16x16x32_bf16 v[64:67], v[138:141], v[178:181], v[64:67]
	v_mfma_f32_16x16x32_bf16 v[60:63], v[146:149], v[178:181], v[60:63]
	v_mfma_f32_16x16x32_bf16 v[56:59], v[138:141], v[234:237], v[56:59]
	v_mfma_f32_16x16x32_bf16 v[52:55], v[146:149], v[234:237], v[52:55]
	v_mfma_f32_16x16x32_bf16 v[48:51], v[138:141], v[242:245], v[48:51]
	v_mfma_f32_16x16x32_bf16 v[12:15], v[146:149], v[242:245], v[12:15]
	v_mfma_f32_16x16x32_bf16 v[44:47], v[150:153], v[166:169], v[44:47]
	v_mfma_f32_16x16x32_bf16 v[40:43], v[158:161], v[166:169], v[40:43]
	v_mfma_f32_16x16x32_bf16 v[36:39], v[150:153], v[174:177], v[36:39]
	v_mfma_f32_16x16x32_bf16 v[32:35], v[158:161], v[174:177], v[32:35]
	v_mfma_f32_16x16x32_bf16 v[28:31], v[150:153], v[230:233], v[28:31]
	v_mfma_f32_16x16x32_bf16 v[24:27], v[158:161], v[230:233], v[24:27]
	v_mfma_f32_16x16x32_bf16 v[20:23], v[150:153], v[238:241], v[20:23]
	v_mfma_f32_16x16x32_bf16 v[16:19], v[158:161], v[238:241], v[16:19]
	v_mfma_f32_16x16x32_bf16 v[44:47], v[154:157], v[170:173], v[44:47]
	v_mfma_f32_16x16x32_bf16 v[40:43], v[162:165], v[170:173], v[40:43]
	v_mfma_f32_16x16x32_bf16 v[36:39], v[154:157], v[178:181], v[36:39]
	v_mfma_f32_16x16x32_bf16 v[32:35], v[162:165], v[178:181], v[32:35]
	v_mfma_f32_16x16x32_bf16 v[28:31], v[154:157], v[234:237], v[28:31]
	v_mfma_f32_16x16x32_bf16 v[24:27], v[162:165], v[234:237], v[24:27]
	v_mfma_f32_16x16x32_bf16 v[20:23], v[154:157], v[242:245], v[20:23]
	v_mfma_f32_16x16x32_bf16 v[16:19], v[162:165], v[242:245], v[16:19]
	s_setprio 0
	s_barrier
	s_add_i32 s26, 0, 0x18000
	s_add_i32 s27, 0, 0x1c000
	v_add_u32_e32 v146, s26, v226
	v_add_u32_e32 v162, s27, v226
	ds_read_b128 v[134:137], v146
	ds_read_b128 v[138:141], v146 offset:1024
	ds_read_b128 v[142:145], v146 offset:2048
	ds_read_b128 v[146:149], v146 offset:3072
	ds_read_b128 v[150:153], v162
	ds_read_b128 v[154:157], v162 offset:1024
	ds_read_b128 v[158:161], v162 offset:2048
	ds_read_b128 v[162:165], v162 offset:3072
	s_add_u32 s8, s8, s10
	s_addc_u32 s9, s9, 0
	s_mov_b32 m0, s51
	v_lshl_add_u64 v[214:215], s[8:9], 0, v[190:191]
	ds_read_b128 v[166:169], v227 offset:32768
	ds_read_b128 v[170:173], v227 offset:33792
	ds_read_b128 v[174:177], v227 offset:34816
	ds_read_b128 v[178:181], v227 offset:35840
	ds_read_b128 v[230:233], v227 offset:36864
	ds_read_b128 v[234:237], v227 offset:37888
	ds_read_b128 v[238:241], v227 offset:38912
	ds_read_b128 v[242:245], v227 offset:39936
	global_load_lds_dwordx4 v[214:215], off
	v_lshl_add_u64 v[214:215], s[8:9], 0, v[194:195]
	s_mov_b32 m0, s62
	s_nop 0
	global_load_lds_dwordx4 v[214:215], off
	s_waitcnt vmcnt(8)
	s_waitcnt lgkmcnt(0)
	s_barrier
	s_setprio 1
	s_waitcnt lgkmcnt(0)
	v_mfma_f32_16x16x32_bf16 v[124:127], v[134:137], v[166:169], v[124:127]
	v_mfma_f32_16x16x32_bf16 v[0:3], v[142:145], v[166:169], v[0:3]
	v_mfma_f32_16x16x32_bf16 v[120:123], v[134:137], v[174:177], v[120:123]
	v_mfma_f32_16x16x32_bf16 v[116:119], v[142:145], v[174:177], v[116:119]
	v_mfma_f32_16x16x32_bf16 v[112:115], v[134:137], v[230:233], v[112:115]
	v_mfma_f32_16x16x32_bf16 v[108:111], v[142:145], v[230:233], v[108:111]
	v_mfma_f32_16x16x32_bf16 v[104:107], v[134:137], v[238:241], v[104:107]
	v_mfma_f32_16x16x32_bf16 v[4:7], v[142:145], v[238:241], v[4:7]
	v_mfma_f32_16x16x32_bf16 v[124:127], v[138:141], v[170:173], v[124:127]
	v_mfma_f32_16x16x32_bf16 v[0:3], v[146:149], v[170:173], v[0:3]
	v_mfma_f32_16x16x32_bf16 v[120:123], v[138:141], v[178:181], v[120:123]
	v_mfma_f32_16x16x32_bf16 v[116:119], v[146:149], v[178:181], v[116:119]
	v_mfma_f32_16x16x32_bf16 v[112:115], v[138:141], v[234:237], v[112:115]
	v_mfma_f32_16x16x32_bf16 v[108:111], v[146:149], v[234:237], v[108:111]
	v_mfma_f32_16x16x32_bf16 v[104:107], v[138:141], v[242:245], v[104:107]
	v_mfma_f32_16x16x32_bf16 v[4:7], v[146:149], v[242:245], v[4:7]
	v_mfma_f32_16x16x32_bf16 v[100:103], v[150:153], v[166:169], v[100:103]
	v_mfma_f32_16x16x32_bf16 v[96:99], v[158:161], v[166:169], v[96:99]
	v_mfma_f32_16x16x32_bf16 v[92:95], v[150:153], v[174:177], v[92:95]
	v_mfma_f32_16x16x32_bf16 v[88:91], v[158:161], v[174:177], v[88:91]
	v_mfma_f32_16x16x32_bf16 v[84:87], v[150:153], v[230:233], v[84:87]
	v_mfma_f32_16x16x32_bf16 v[80:83], v[158:161], v[230:233], v[80:83]
	v_mfma_f32_16x16x32_bf16 v[76:79], v[150:153], v[238:241], v[76:79]
	v_mfma_f32_16x16x32_bf16 v[72:75], v[158:161], v[238:241], v[72:75]
	v_mfma_f32_16x16x32_bf16 v[100:103], v[154:157], v[170:173], v[100:103]
	v_mfma_f32_16x16x32_bf16 v[96:99], v[162:165], v[170:173], v[96:99]
	v_mfma_f32_16x16x32_bf16 v[92:95], v[154:157], v[178:181], v[92:95]
	v_mfma_f32_16x16x32_bf16 v[88:91], v[162:165], v[178:181], v[88:91]
	v_mfma_f32_16x16x32_bf16 v[84:87], v[154:157], v[234:237], v[84:87]
	v_mfma_f32_16x16x32_bf16 v[80:83], v[162:165], v[234:237], v[80:83]
	v_mfma_f32_16x16x32_bf16 v[76:79], v[154:157], v[242:245], v[76:79]
	v_mfma_f32_16x16x32_bf16 v[72:75], v[162:165], v[242:245], v[72:75]
	s_setprio 0
	s_barrier
; #define PG8_STAGE(bufoff, gbase, voff) do { _Pragma("unroll") for (int _i = 0; _i < 2; ++_i) \
;         __builtin_amdgcn_global_load_lds((const unsigned*)((const char*)(gbase) + (voff)[_i]), (LAS unsigned*)(lds + (bufoff) + ldsw + _i * 8192), 16, 0, 0); } while (0)
; #define PG8_LDA(dst, b, h) do { _Pragma("unroll") for (int m = 0; m < 4; ++m) _Pragma("unroll") for (int k = 0; k < 2; ++k) dst[m][k] = *(const LAS bf16x8*)(lds + PG8_SA(b, h) + aoff + m * 2048 + k * 1024); } while (0)
; #define PG8_MMA(ai, bj, At, Bt) do { __builtin_amdgcn_s_setprio(1); _Pragma("unroll") for (int m = 0; m < 4; ++m) _Pragma("unroll") for (int n = 0; n < 2; ++n) _Pragma("unroll") for (int k = 0; k < 2; ++k) \
;         acc[ai][bj][m][n] = __builtin_amdgcn_mfma_f32_16x16x32_bf16(Bt[n][k], At[m][k], acc[ai][bj][m][n], 0, 0, 0); __builtin_amdgcn_s_setprio(0); } while (0)
; #define PG8_WAIT_V(n) asm volatile("s_waitcnt vmcnt(" #n ")" ::: "memory")
; #define PG8_WAIT_L(n) asm volatile("s_waitcnt lgkmcnt(" #n ")" ::: "memory")
; #define PG8_BAR __builtin_amdgcn_s_barrier()
; #define PG8_SCHED __builtin_amdgcn_sched_barrier(0)
;     ...
;             PG8_LDA(At, 1, 1); PG8_STAGE(PG8_SB(1, 0), b3, voffB); PG8_STAGE(PG8_SB(1, 1), b3 + hstepB, voffB); PG8_STAGE(PG8_SA(1, 0), a3, voffA);
;             PG8_WAIT_V(8); PG8_WAIT_L(0); PG8_BAR; PG8_MMA(1, 0, At, B0); PG8_MMA(1, 1, At, B1); PG8_BAR; PG8_SCHED;
;         }
;         if (wr == 0) PG8_BAR;
	s_add_i32 s8, s26, s11
	s_add_i32 m0, s8, 0xffffff80
	ds_read_b128 v[166:169], v227 offset:49152
	ds_read_b128 v[170:173], v227 offset:50176
	ds_read_b128 v[174:177], v227 offset:51200
	ds_read_b128 v[178:181], v227 offset:52224
	ds_read_b128 v[230:233], v227 offset:53248
	ds_read_b128 v[234:237], v227 offset:54272
	ds_read_b128 v[238:241], v227 offset:55296
	ds_read_b128 v[242:245], v227 offset:56320
	global_load_lds_dwordx4 v[212:213], off offset:128
	s_add_i32 m0, s8, 0x1f80
	s_add_i32 s8, s27, s11
	global_load_lds_dwordx4 v[218:219], off offset:128
	s_add_i32 m0, s8, 0xffffff80
	s_nop 0
	global_load_lds_dwordx4 v[246:247], off offset:128
	s_add_i32 m0, s8, 0x1f80
	s_nop 0
	global_load_lds_dwordx4 v[204:205], off offset:128
	s_add_i32 m0, s65, 0xffffff80
	s_nop 0
	global_load_lds_dwordx4 v[248:249], off offset:128
	s_add_i32 m0, s49, 0xffffff80
	s_nop 0
	global_load_lds_dwordx4 v[250:251], off offset:128
	s_waitcnt vmcnt(8)
	s_waitcnt lgkmcnt(0)
	s_barrier
	s_setprio 1
	s_waitcnt lgkmcnt(0)
	v_mfma_f32_16x16x32_bf16 v[68:71], v[134:137], v[166:169], v[68:71]
	v_mfma_f32_16x16x32_bf16 v[8:11], v[142:145], v[166:169], v[8:11]
	v_mfma_f32_16x16x32_bf16 v[64:67], v[134:137], v[174:177], v[64:67]
	v_mfma_f32_16x16x32_bf16 v[60:63], v[142:145], v[174:177], v[60:63]
	v_mfma_f32_16x16x32_bf16 v[56:59], v[134:137], v[230:233], v[56:59]
	v_mfma_f32_16x16x32_bf16 v[52:55], v[142:145], v[230:233], v[52:55]
	v_mfma_f32_16x16x32_bf16 v[48:51], v[134:137], v[238:241], v[48:51]
	v_mfma_f32_16x16x32_bf16 v[12:15], v[142:145], v[238:241], v[12:15]
	v_mfma_f32_16x16x32_bf16 v[68:71], v[138:141], v[170:173], v[68:71]
	v_mfma_f32_16x16x32_bf16 v[8:11], v[146:149], v[170:173], v[8:11]
	v_mfma_f32_16x16x32_bf16 v[64:67], v[138:141], v[178:181], v[64:67]
	v_mfma_f32_16x16x32_bf16 v[60:63], v[146:149], v[178:181], v[60:63]
	v_mfma_f32_16x16x32_bf16 v[56:59], v[138:141], v[234:237], v[56:59]
	v_mfma_f32_16x16x32_bf16 v[52:55], v[146:149], v[234:237], v[52:55]
	v_mfma_f32_16x16x32_bf16 v[48:51], v[138:141], v[242:245], v[48:51]
	v_mfma_f32_16x16x32_bf16 v[12:15], v[146:149], v[242:245], v[12:15]
	v_mfma_f32_16x16x32_bf16 v[44:47], v[150:153], v[166:169], v[44:47]
	v_mfma_f32_16x16x32_bf16 v[40:43], v[158:161], v[166:169], v[40:43]
	v_mfma_f32_16x16x32_bf16 v[36:39], v[150:153], v[174:177], v[36:39]
	v_mfma_f32_16x16x32_bf16 v[32:35], v[158:161], v[174:177], v[32:35]
	v_mfma_f32_16x16x32_bf16 v[28:31], v[150:153], v[230:233], v[28:31]
	v_mfma_f32_16x16x32_bf16 v[24:27], v[158:161], v[230:233], v[24:27]
	v_mfma_f32_16x16x32_bf16 v[20:23], v[150:153], v[238:241], v[20:23]
	v_mfma_f32_16x16x32_bf16 v[16:19], v[158:161], v[238:241], v[16:19]
	v_mfma_f32_16x16x32_bf16 v[44:47], v[154:157], v[170:173], v[44:47]
	v_mfma_f32_16x16x32_bf16 v[40:43], v[162:165], v[170:173], v[40:43]
	v_mfma_f32_16x16x32_bf16 v[36:39], v[154:157], v[178:181], v[36:39]
	v_mfma_f32_16x16x32_bf16 v[32:35], v[162:165], v[178:181], v[32:35]
	v_mfma_f32_16x16x32_bf16 v[28:31], v[154:157], v[234:237], v[28:31]
	v_mfma_f32_16x16x32_bf16 v[24:27], v[162:165], v[234:237], v[24:27]
	v_mfma_f32_16x16x32_bf16 v[20:23], v[154:157], v[242:245], v[20:23]
	v_mfma_f32_16x16x32_bf16 v[16:19], v[162:165], v[242:245], v[16:19]
	s_setprio 0
	s_barrier
	s_add_u32 s0, s0, 0x100
	s_addc_u32 s1, s1, 0
	v_lshl_add_u64 v[130:131], v[130:131], 0, s[94:95]
	v_lshl_add_u64 v[128:129], v[128:129], 0, s[94:95]
	s_cmp_ge_u32 s38, s52
	s_mov_b32 s8, s38
	s_cbranch_scc0 .LBB0_159
	v_readlane_b32 s0, v254, 50
	v_readlane_b32 s1, v254, 51
	s_and_b64 vcc, exec, s[0:1]
	s_movk_i32 s67, 0xfe
	s_cbranch_vccz .LBB0_162
	s_barrier

; #define PG8_STAGE(bufoff, gbase, voff) do { _Pragma("unroll") for (int _i = 0; _i < 2; ++_i) \
;         __builtin_amdgcn_global_load_lds((const unsigned*)((const char*)(gbase) + (voff)[_i]), (LAS unsigned*)(lds + (bufoff) + ldsw + _i * 8192), 16, 0, 0); } while (0)
; #define PG8_LDA(dst, b, h) do { _Pragma("unroll") for (int m = 0; m < 4; ++m) _Pragma("unroll") for (int k = 0; k < 2; ++k) dst[m][k] = *(const LAS bf16x8*)(lds + PG8_SA(b, h) + aoff + m * 2048 + k * 1024); } while (0)
; #define PG8_LDB(dst, b, h) do { _Pragma("unroll") for (int n = 0; n < 2; ++n) _Pragma("unroll") for (int k = 0; k < 2; ++k) dst[n][k] = *(const LAS bf16x8*)(lds + PG8_SB(b, h) + boff + n * 2048 + k * 1024); } while (0)
; #define PG8_MMA(ai, bj, At, Bt) do { __builtin_amdgcn_s_setprio(1); _Pragma("unroll") for (int m = 0; m < 4; ++m) _Pragma("unroll") for (int n = 0; n < 2; ++n) _Pragma("unroll") for (int k = 0; k < 2; ++k) \
;         acc[ai][bj][m][n] = __builtin_amdgcn_mfma_f32_16x16x32_bf16(Bt[n][k], At[m][k], acc[ai][bj][m][n], 0, 0, 0); __builtin_amdgcn_s_setprio(0); } while (0)
; #define PG8_WAIT_V(n) asm volatile("s_waitcnt vmcnt(" #n ")" ::: "memory")
; #define PG8_WAIT_L(n) asm volatile("s_waitcnt lgkmcnt(" #n ")" ::: "memory")
; #define PG8_BAR __builtin_amdgcn_s_barrier()
; #define PG8_SCHED __builtin_amdgcn_sched_barrier(0)
;     ...
;         for (int t = 0; t < nt; t += 2) {
;             const bool last = (t == nt - 2);
;             const char* a1 = cA + (size_t)(t + 1) * kstep;
;             const char* a2 = last ? nA : cA + (size_t)(t + 2) * kstep; const char* b2 = last ? nB : cB + (size_t)(t + 2) * kstep;
;             const char* a3 = a2 + kstep; const char* b3 = b2 + kstep;
;             PG8_LDB(B0, 0, 0); PG8_LDB(B1, 0, 1); PG8_SCHED; PG8_LDA(At, 0, 0); PG8_STAGE(PG8_SA(1, 1), a1 + hstepA, voffA);
;             PG8_WAIT_V(8); PG8_WAIT_L(0); PG8_BAR; PG8_MMA(0, 0, At, B0); PG8_MMA(0, 1, At, B1); PG8_BAR; PG8_SCHED;
;             PG8_LDA(At, 0, 1); PG8_STAGE(PG8_SB(0, 0), b2, voffB); PG8_STAGE(PG8_SB(0, 1), b2 + hstepB, voffB); PG8_STAGE(PG8_SA(0, 0), a2, voffA);
;             PG8_WAIT_V(8); PG8_WAIT_L(0); PG8_BAR; PG8_MMA(1, 0, At, B0); PG8_MMA(1, 1, At, B1); PG8_BAR; PG8_SCHED;
.LBB0_318:
	s_add_i32 s57, s38, 2
	s_add_u32 s19, s2, s0
	s_addc_u32 s27, s3, s1
	s_add_i32 s58, 0, 0x10000
	s_cmp_eq_u32 s51, s38
	s_cselect_b32 s39, s13, s27
	s_cselect_b32 s38, s56, s19
	s_cselect_b64 vcc, -1, 0
	s_add_i32 s19, 0, 0x14000
	v_lshl_add_u64 v[150:151], v[160:161], 0, s[0:1]
	v_add_u32_e32 v146, s58, v181
	s_waitcnt lgkmcnt(0)
	v_add_u32_e32 v178, s19, v181
	ds_read_b128 v[134:137], v146
	ds_read_b128 v[138:141], v146 offset:1024
	ds_read_b128 v[142:145], v146 offset:2048
	ds_read_b128 v[146:149], v146 offset:3072
	v_cndmask_b32_e32 v159, v151, v132, vcc
	v_cndmask_b32_e32 v158, v150, v133, vcc
	ds_read_b128 v[150:153], v178
	ds_read_b128 v[154:157], v178 offset:1024
	ds_read_b128 v[174:177], v178 offset:2048
	ds_read_b128 v[190:193], v178 offset:3072
	v_lshl_add_u64 v[178:179], s[2:3], 0, v[130:131]
	s_add_i32 m0, s11, 0xc000
	ds_read_b128 v[194:197], v188
	ds_read_b128 v[198:201], v188 offset:1024
	ds_read_b128 v[202:205], v188 offset:2048
	ds_read_b128 v[224:227], v188 offset:3072
	ds_read_b128 v[228:231], v188 offset:4096
	ds_read_b128 v[232:235], v188 offset:5120
	ds_read_b128 v[236:239], v188 offset:6144
	ds_read_b128 v[240:243], v188 offset:7168
	global_load_lds_dwordx4 v[178:179], off
	v_lshl_add_u64 v[178:179], s[2:3], 0, v[128:129]
	s_add_i32 m0, s11, 0xe000
	s_nop 0
	global_load_lds_dwordx4 v[178:179], off
	s_waitcnt vmcnt(8)
	s_waitcnt lgkmcnt(0)
	s_barrier
	s_setprio 1
	s_waitcnt lgkmcnt(0)
	v_mfma_f32_16x16x32_bf16 v[124:127], v[134:137], v[194:197], v[124:127]
	v_mfma_f32_16x16x32_bf16 v[120:123], v[142:145], v[194:197], v[120:123]
	v_mfma_f32_16x16x32_bf16 v[116:119], v[134:137], v[202:205], v[116:119]
	v_mfma_f32_16x16x32_bf16 v[112:115], v[142:145], v[202:205], v[112:115]
	v_mfma_f32_16x16x32_bf16 v[108:111], v[134:137], v[228:231], v[108:111]
	v_mfma_f32_16x16x32_bf16 v[104:107], v[142:145], v[228:231], v[104:107]
	v_lshl_add_u64 v[178:179], v[158:159], 0, v[164:165]
	v_mfma_f32_16x16x32_bf16 v[100:103], v[134:137], v[236:239], v[100:103]
	v_mfma_f32_16x16x32_bf16 v[96:99], v[142:145], v[236:239], v[96:99]
	v_lshl_add_u64 v[212:213], v[158:159], 0, v[168:169]
	v_mfma_f32_16x16x32_bf16 v[124:127], v[138:141], v[198:201], v[124:127]
	v_mfma_f32_16x16x32_bf16 v[120:123], v[146:149], v[198:201], v[120:123]
	v_lshl_add_u64 v[158:159], v[158:159], 0, s[96:97]
	v_mfma_f32_16x16x32_bf16 v[116:119], v[138:141], v[224:227], v[116:119]
	v_mfma_f32_16x16x32_bf16 v[112:115], v[146:149], v[224:227], v[112:115]
	v_lshl_add_u64 v[218:219], v[158:159], 0, v[164:165]
	v_mfma_f32_16x16x32_bf16 v[108:111], v[138:141], v[232:235], v[108:111]
	v_mfma_f32_16x16x32_bf16 v[104:107], v[146:149], v[232:235], v[104:107]
	v_lshl_add_u64 v[158:159], v[158:159], 0, v[168:169]
	v_mfma_f32_16x16x32_bf16 v[100:103], v[138:141], v[240:243], v[100:103]
	v_mfma_f32_16x16x32_bf16 v[96:99], v[146:149], v[240:243], v[96:99]
	v_lshl_add_u64 v[244:245], s[38:39], 0, v[162:163]
	v_mfma_f32_16x16x32_bf16 v[92:95], v[150:153], v[194:197], v[92:95]
	v_mfma_f32_16x16x32_bf16 v[88:91], v[174:177], v[194:197], v[88:91]
	v_lshl_add_u64 v[246:247], s[38:39], 0, v[166:167]
	v_mfma_f32_16x16x32_bf16 v[84:87], v[150:153], v[202:205], v[84:87]
	v_mfma_f32_16x16x32_bf16 v[80:83], v[174:177], v[202:205], v[80:83]
	v_mfma_f32_16x16x32_bf16 v[76:79], v[150:153], v[228:231], v[76:79]
	v_mfma_f32_16x16x32_bf16 v[72:75], v[174:177], v[228:231], v[72:75]
	v_mfma_f32_16x16x32_bf16 v[68:71], v[150:153], v[236:239], v[68:71]
	v_mfma_f32_16x16x32_bf16 v[64:67], v[174:177], v[236:239], v[64:67]
	v_mfma_f32_16x16x32_bf16 v[92:95], v[154:157], v[198:201], v[92:95]
	v_mfma_f32_16x16x32_bf16 v[88:91], v[190:193], v[198:201], v[88:91]
	v_mfma_f32_16x16x32_bf16 v[84:87], v[154:157], v[224:227], v[84:87]
	v_mfma_f32_16x16x32_bf16 v[80:83], v[190:193], v[224:227], v[80:83]
	v_mfma_f32_16x16x32_bf16 v[76:79], v[154:157], v[232:235], v[76:79]
	v_mfma_f32_16x16x32_bf16 v[72:75], v[190:193], v[232:235], v[72:75]
	v_mfma_f32_16x16x32_bf16 v[68:71], v[154:157], v[240:243], v[68:71]
	v_mfma_f32_16x16x32_bf16 v[64:67], v[190:193], v[240:243], v[64:67]
	s_setprio 0
	s_barrier
	s_add_i32 s27, s58, s10
	s_mov_b32 m0, s27
	ds_read_b128 v[194:197], v188 offset:16384
	ds_read_b128 v[198:201], v188 offset:17408
	ds_read_b128 v[202:205], v188 offset:18432
	ds_read_b128 v[224:227], v188 offset:19456
	ds_read_b128 v[228:231], v188 offset:20480
	ds_read_b128 v[232:235], v188 offset:21504
	ds_read_b128 v[236:239], v188 offset:22528
	ds_read_b128 v[240:243], v188 offset:23552
	global_load_lds_dwordx4 v[178:179], off
	s_add_i32 m0, s27, 0x2000
	s_add_i32 s19, s19, s10
	global_load_lds_dwordx4 v[212:213], off
	s_mov_b32 m0, s19
	s_nop 0
	global_load_lds_dwordx4 v[218:219], off
	s_add_i32 m0, s19, 0x2000
	s_nop 0
	global_load_lds_dwordx4 v[158:159], off
	s_mov_b32 m0, s11
	s_nop 0
	global_load_lds_dwordx4 v[244:245], off
	s_mov_b32 m0, s20
	s_nop 0
	global_load_lds_dwordx4 v[246:247], off
	s_waitcnt vmcnt(8)
	s_waitcnt lgkmcnt(0)
	s_barrier
; #define PG8_STAGE(bufoff, gbase, voff) do { _Pragma("unroll") for (int _i = 0; _i < 2; ++_i) \
;         __builtin_amdgcn_global_load_lds((const unsigned*)((const char*)(gbase) + (voff)[_i]), (LAS unsigned*)(lds + (bufoff) + ldsw + _i * 8192), 16, 0, 0); } while (0)
; #define PG8_LDA(dst, b, h) do { _Pragma("unroll") for (int m = 0; m < 4; ++m) _Pragma("unroll") for (int k = 0; k < 2; ++k) dst[m][k] = *(const LAS bf16x8*)(lds + PG8_SA(b, h) + aoff + m * 2048 + k * 1024); } while (0)
; #define PG8_LDB(dst, b, h) do { _Pragma("unroll") for (int n = 0; n < 2; ++n) _Pragma("unroll") for (int k = 0; k < 2; ++k) dst[n][k] = *(const LAS bf16x8*)(lds + PG8_SB(b, h) + boff + n * 2048 + k * 1024); } while (0)
; #define PG8_MMA(ai, bj, At, Bt) do { __builtin_amdgcn_s_setprio(1); _Pragma("unroll") for (int m = 0; m < 4; ++m) _Pragma("unroll") for (int n = 0; n < 2; ++n) _Pragma("unroll") for (int k = 0; k < 2; ++k) \
;         acc[ai][bj][m][n] = __builtin_amdgcn_mfma_f32_16x16x32_bf16(Bt[n][k], At[m][k], acc[ai][bj][m][n], 0, 0, 0); __builtin_amdgcn_s_setprio(0); } while (0)
; #define PG8_WAIT_V(n) asm volatile("s_waitcnt vmcnt(" #n ")" ::: "memory")
; #define PG8_WAIT_L(n) asm volatile("s_waitcnt lgkmcnt(" #n ")" ::: "memory")
; #define PG8_BAR __builtin_amdgcn_s_barrier()
; #define PG8_SCHED __builtin_amdgcn_sched_barrier(0)
;     ...
;             PG8_WAIT_V(8); PG8_WAIT_L(0); PG8_BAR; PG8_MMA(1, 0, At, B0); PG8_MMA(1, 1, At, B1); PG8_BAR; PG8_SCHED;
;             PG8_LDB(B0, 1, 0); PG8_LDB(B1, 1, 1); PG8_SCHED; PG8_LDA(At, 1, 0); PG8_STAGE(PG8_SA(0, 1), a2 + hstepA, voffA);
;             PG8_WAIT_V(8); PG8_WAIT_L(0); PG8_BAR; PG8_MMA(0, 0, At, B0); PG8_MMA(0, 1, At, B1); PG8_BAR; PG8_SCHED;
	s_setprio 1
	s_waitcnt lgkmcnt(0)
	v_mfma_f32_16x16x32_bf16 v[60:63], v[134:137], v[194:197], v[60:63]
	v_mfma_f32_16x16x32_bf16 v[56:59], v[142:145], v[194:197], v[56:59]
	v_mfma_f32_16x16x32_bf16 v[52:55], v[134:137], v[202:205], v[52:55]
	v_mfma_f32_16x16x32_bf16 v[48:51], v[142:145], v[202:205], v[48:51]
	v_mfma_f32_16x16x32_bf16 v[44:47], v[134:137], v[228:231], v[44:47]
	v_mfma_f32_16x16x32_bf16 v[40:43], v[142:145], v[228:231], v[40:43]
	v_mfma_f32_16x16x32_bf16 v[36:39], v[134:137], v[236:239], v[36:39]
	v_mfma_f32_16x16x32_bf16 v[32:35], v[142:145], v[236:239], v[32:35]
	v_mfma_f32_16x16x32_bf16 v[60:63], v[138:141], v[198:201], v[60:63]
	v_mfma_f32_16x16x32_bf16 v[56:59], v[146:149], v[198:201], v[56:59]
	v_mfma_f32_16x16x32_bf16 v[52:55], v[138:141], v[224:227], v[52:55]
	v_mfma_f32_16x16x32_bf16 v[48:51], v[146:149], v[224:227], v[48:51]
	v_mfma_f32_16x16x32_bf16 v[44:47], v[138:141], v[232:235], v[44:47]
	v_mfma_f32_16x16x32_bf16 v[40:43], v[146:149], v[232:235], v[40:43]
	v_mfma_f32_16x16x32_bf16 v[36:39], v[138:141], v[240:243], v[36:39]
	v_mfma_f32_16x16x32_bf16 v[32:35], v[146:149], v[240:243], v[32:35]
	v_mfma_f32_16x16x32_bf16 v[28:31], v[150:153], v[194:197], v[28:31]
	v_mfma_f32_16x16x32_bf16 v[24:27], v[174:177], v[194:197], v[24:27]
	v_mfma_f32_16x16x32_bf16 v[20:23], v[150:153], v[202:205], v[20:23]
	v_mfma_f32_16x16x32_bf16 v[16:19], v[174:177], v[202:205], v[16:19]
	v_mfma_f32_16x16x32_bf16 v[12:15], v[150:153], v[228:231], v[12:15]
	v_mfma_f32_16x16x32_bf16 v[8:11], v[174:177], v[228:231], v[8:11]
	v_mfma_f32_16x16x32_bf16 v[4:7], v[150:153], v[236:239], v[4:7]
	v_mfma_f32_16x16x32_bf16 v[0:3], v[174:177], v[236:239], v[0:3]
	v_mfma_f32_16x16x32_bf16 v[28:31], v[154:157], v[198:201], v[28:31]
	v_mfma_f32_16x16x32_bf16 v[24:27], v[190:193], v[198:201], v[24:27]
	v_mfma_f32_16x16x32_bf16 v[20:23], v[154:157], v[224:227], v[20:23]
	v_mfma_f32_16x16x32_bf16 v[16:19], v[190:193], v[224:227], v[16:19]
	v_mfma_f32_16x16x32_bf16 v[12:15], v[154:157], v[232:235], v[12:15]
	v_mfma_f32_16x16x32_bf16 v[8:11], v[190:193], v[232:235], v[8:11]
	v_mfma_f32_16x16x32_bf16 v[4:7], v[154:157], v[240:243], v[4:7]
	v_mfma_f32_16x16x32_bf16 v[0:3], v[190:193], v[240:243], v[0:3]
	s_setprio 0
	s_barrier
	s_add_i32 s19, 0, 0x18000
	s_add_i32 s27, 0, 0x1c000
	v_add_u32_e32 v146, s19, v181
	v_add_u32_e32 v182, s27, v181
	ds_read_b128 v[134:137], v146
	ds_read_b128 v[138:141], v146 offset:1024
	ds_read_b128 v[142:145], v146 offset:2048
	ds_read_b128 v[146:149], v146 offset:3072
	ds_read_b128 v[150:153], v182
	ds_read_b128 v[154:157], v182 offset:1024
	ds_read_b128 v[174:177], v182 offset:2048
	ds_read_b128 v[190:193], v182 offset:3072
	s_add_u32 s38, s38, s96
	s_addc_u32 s39, s39, 0
	s_mov_b32 m0, s48
	v_lshl_add_u64 v[248:249], s[38:39], 0, v[162:163]
	ds_read_b128 v[194:197], v188 offset:32768
	ds_read_b128 v[198:201], v188 offset:33792
	ds_read_b128 v[202:205], v188 offset:34816
	ds_read_b128 v[224:227], v188 offset:35840
	ds_read_b128 v[228:231], v188 offset:36864
	ds_read_b128 v[232:235], v188 offset:37888
	ds_read_b128 v[236:239], v188 offset:38912
	ds_read_b128 v[240:243], v188 offset:39936
	global_load_lds_dwordx4 v[248:249], off
	v_lshl_add_u64 v[248:249], s[38:39], 0, v[166:167]
	s_mov_b32 m0, s49
	s_nop 0
	global_load_lds_dwordx4 v[248:249], off
	s_waitcnt vmcnt(8)
	s_waitcnt lgkmcnt(0)
	s_barrier
	s_setprio 1
	s_waitcnt lgkmcnt(0)
	v_mfma_f32_16x16x32_bf16 v[124:127], v[134:137], v[194:197], v[124:127]
	v_mfma_f32_16x16x32_bf16 v[120:123], v[142:145], v[194:197], v[120:123]
	v_mfma_f32_16x16x32_bf16 v[116:119], v[134:137], v[202:205], v[116:119]
	v_mfma_f32_16x16x32_bf16 v[112:115], v[142:145], v[202:205], v[112:115]
	v_mfma_f32_16x16x32_bf16 v[108:111], v[134:137], v[228:231], v[108:111]
	v_mfma_f32_16x16x32_bf16 v[104:107], v[142:145], v[228:231], v[104:107]
	v_mfma_f32_16x16x32_bf16 v[100:103], v[134:137], v[236:239], v[100:103]
	v_mfma_f32_16x16x32_bf16 v[96:99], v[142:145], v[236:239], v[96:99]
	v_mfma_f32_16x16x32_bf16 v[124:127], v[138:141], v[198:201], v[124:127]
	v_mfma_f32_16x16x32_bf16 v[120:123], v[146:149], v[198:201], v[120:123]
	v_mfma_f32_16x16x32_bf16 v[116:119], v[138:141], v[224:227], v[116:119]
	v_mfma_f32_16x16x32_bf16 v[112:115], v[146:149], v[224:227], v[112:115]
	v_mfma_f32_16x16x32_bf16 v[108:111], v[138:141], v[232:235], v[108:111]
	v_mfma_f32_16x16x32_bf16 v[104:107], v[146:149], v[232:235], v[104:107]
	v_mfma_f32_16x16x32_bf16 v[100:103], v[138:141], v[240:243], v[100:103]
	v_mfma_f32_16x16x32_bf16 v[96:99], v[146:149], v[240:243], v[96:99]
	v_mfma_f32_16x16x32_bf16 v[92:95], v[150:153], v[194:197], v[92:95]
	v_mfma_f32_16x16x32_bf16 v[88:91], v[174:177], v[194:197], v[88:91]
	v_mfma_f32_16x16x32_bf16 v[84:87], v[150:153], v[202:205], v[84:87]
	v_mfma_f32_16x16x32_bf16 v[80:83], v[174:177], v[202:205], v[80:83]
	v_mfma_f32_16x16x32_bf16 v[76:79], v[150:153], v[228:231], v[76:79]
	v_mfma_f32_16x16x32_bf16 v[72:75], v[174:177], v[228:231], v[72:75]
	v_mfma_f32_16x16x32_bf16 v[68:71], v[150:153], v[236:239], v[68:71]
	v_mfma_f32_16x16x32_bf16 v[64:67], v[174:177], v[236:239], v[64:67]
	v_mfma_f32_16x16x32_bf16 v[92:95], v[154:157], v[198:201], v[92:95]
	v_mfma_f32_16x16x32_bf16 v[88:91], v[190:193], v[198:201], v[88:91]
	v_mfma_f32_16x16x32_bf16 v[84:87], v[154:157], v[224:227], v[84:87]
	v_mfma_f32_16x16x32_bf16 v[80:83], v[190:193], v[224:227], v[80:83]
	v_mfma_f32_16x16x32_bf16 v[76:79], v[154:157], v[232:235], v[76:79]
	v_mfma_f32_16x16x32_bf16 v[72:75], v[190:193], v[232:235], v[72:75]
	v_mfma_f32_16x16x32_bf16 v[68:71], v[154:157], v[240:243], v[68:71]
	v_mfma_f32_16x16x32_bf16 v[64:67], v[190:193], v[240:243], v[64:67]
	s_setprio 0
	s_barrier
; #define PG8_STAGE(bufoff, gbase, voff) do { _Pragma("unroll") for (int _i = 0; _i < 2; ++_i) \
;         __builtin_amdgcn_global_load_lds((const unsigned*)((const char*)(gbase) + (voff)[_i]), (LAS unsigned*)(lds + (bufoff) + ldsw + _i * 8192), 16, 0, 0); } while (0)
; #define PG8_LDA(dst, b, h) do { _Pragma("unroll") for (int m = 0; m < 4; ++m) _Pragma("unroll") for (int k = 0; k < 2; ++k) dst[m][k] = *(const LAS bf16x8*)(lds + PG8_SA(b, h) + aoff + m * 2048 + k * 1024); } while (0)
; #define PG8_MMA(ai, bj, At, Bt) do { __builtin_amdgcn_s_setprio(1); _Pragma("unroll") for (int m = 0; m < 4; ++m) _Pragma("unroll") for (int n = 0; n < 2; ++n) _Pragma("unroll") for (int k = 0; k < 2; ++k) \
;         acc[ai][bj][m][n] = __builtin_amdgcn_mfma_f32_16x16x32_bf16(Bt[n][k], At[m][k], acc[ai][bj][m][n], 0, 0, 0); __builtin_amdgcn_s_setprio(0); } while (0)
; #define PG8_WAIT_V(n) asm volatile("s_waitcnt vmcnt(" #n ")" ::: "memory")
; #define PG8_WAIT_L(n) asm volatile("s_waitcnt lgkmcnt(" #n ")" ::: "memory")
; #define PG8_BAR __builtin_amdgcn_s_barrier()
; #define PG8_SCHED __builtin_amdgcn_sched_barrier(0)
;     ...
;             PG8_LDA(At, 1, 1); PG8_STAGE(PG8_SB(1, 0), b3, voffB); PG8_STAGE(PG8_SB(1, 1), b3 + hstepB, voffB); PG8_STAGE(PG8_SA(1, 0), a3, voffA);
;             PG8_WAIT_V(8); PG8_WAIT_L(0); PG8_BAR; PG8_MMA(1, 0, At, B0); PG8_MMA(1, 1, At, B1); PG8_BAR; PG8_SCHED;
;         }
;         if (wr == 0) PG8_BAR;
	s_add_i32 s19, s19, s10
	s_add_i32 m0, s19, 0xffffff80
	ds_read_b128 v[194:197], v188 offset:49152
	ds_read_b128 v[198:201], v188 offset:50176
	ds_read_b128 v[202:205], v188 offset:51200
	ds_read_b128 v[224:227], v188 offset:52224
	ds_read_b128 v[228:231], v188 offset:53248
	ds_read_b128 v[232:235], v188 offset:54272
	ds_read_b128 v[236:239], v188 offset:55296
	ds_read_b128 v[240:243], v188 offset:56320
	global_load_lds_dwordx4 v[178:179], off offset:128
	s_add_i32 m0, s19, 0x1f80
	s_add_i32 s19, s27, s10
	global_load_lds_dwordx4 v[212:213], off offset:128
	s_add_i32 m0, s19, 0xffffff80
	s_nop 0
	global_load_lds_dwordx4 v[218:219], off offset:128
	s_add_i32 m0, s19, 0x1f80
	s_nop 0
	global_load_lds_dwordx4 v[158:159], off offset:128
	s_add_i32 m0, s62, 0xffffff80
	s_nop 0
	global_load_lds_dwordx4 v[244:245], off offset:128
	s_add_i32 m0, s63, 0xffffff80
	s_nop 0
	global_load_lds_dwordx4 v[246:247], off offset:128
	s_waitcnt vmcnt(8)
	s_waitcnt lgkmcnt(0)
	s_barrier
	s_setprio 1
	s_waitcnt lgkmcnt(0)
	v_mfma_f32_16x16x32_bf16 v[60:63], v[134:137], v[194:197], v[60:63]
	v_mfma_f32_16x16x32_bf16 v[56:59], v[142:145], v[194:197], v[56:59]
	v_mfma_f32_16x16x32_bf16 v[52:55], v[134:137], v[202:205], v[52:55]
	v_mfma_f32_16x16x32_bf16 v[48:51], v[142:145], v[202:205], v[48:51]
	v_mfma_f32_16x16x32_bf16 v[44:47], v[134:137], v[228:231], v[44:47]
	v_mfma_f32_16x16x32_bf16 v[40:43], v[142:145], v[228:231], v[40:43]
	v_mfma_f32_16x16x32_bf16 v[36:39], v[134:137], v[236:239], v[36:39]
	v_mfma_f32_16x16x32_bf16 v[32:35], v[142:145], v[236:239], v[32:35]
	v_mfma_f32_16x16x32_bf16 v[60:63], v[138:141], v[198:201], v[60:63]
	v_mfma_f32_16x16x32_bf16 v[56:59], v[146:149], v[198:201], v[56:59]
	v_mfma_f32_16x16x32_bf16 v[52:55], v[138:141], v[224:227], v[52:55]
	v_mfma_f32_16x16x32_bf16 v[48:51], v[146:149], v[224:227], v[48:51]
	v_mfma_f32_16x16x32_bf16 v[44:47], v[138:141], v[232:235], v[44:47]
	v_mfma_f32_16x16x32_bf16 v[40:43], v[146:149], v[232:235], v[40:43]
	v_mfma_f32_16x16x32_bf16 v[36:39], v[138:141], v[240:243], v[36:39]
	v_mfma_f32_16x16x32_bf16 v[32:35], v[146:149], v[240:243], v[32:35]
	v_mfma_f32_16x16x32_bf16 v[28:31], v[150:153], v[194:197], v[28:31]
	v_mfma_f32_16x16x32_bf16 v[24:27], v[174:177], v[194:197], v[24:27]
	v_mfma_f32_16x16x32_bf16 v[20:23], v[150:153], v[202:205], v[20:23]
	v_mfma_f32_16x16x32_bf16 v[16:19], v[174:177], v[202:205], v[16:19]
	v_mfma_f32_16x16x32_bf16 v[12:15], v[150:153], v[228:231], v[12:15]
	v_mfma_f32_16x16x32_bf16 v[8:11], v[174:177], v[228:231], v[8:11]
	v_mfma_f32_16x16x32_bf16 v[4:7], v[150:153], v[236:239], v[4:7]
	v_mfma_f32_16x16x32_bf16 v[0:3], v[174:177], v[236:239], v[0:3]
	v_mfma_f32_16x16x32_bf16 v[28:31], v[154:157], v[198:201], v[28:31]
	v_mfma_f32_16x16x32_bf16 v[24:27], v[190:193], v[198:201], v[24:27]
	v_mfma_f32_16x16x32_bf16 v[20:23], v[154:157], v[224:227], v[20:23]
	v_mfma_f32_16x16x32_bf16 v[16:19], v[190:193], v[224:227], v[16:19]
	v_mfma_f32_16x16x32_bf16 v[12:15], v[154:157], v[232:235], v[12:15]
	v_mfma_f32_16x16x32_bf16 v[8:11], v[190:193], v[232:235], v[8:11]
	v_mfma_f32_16x16x32_bf16 v[4:7], v[154:157], v[240:243], v[4:7]
	v_mfma_f32_16x16x32_bf16 v[0:3], v[190:193], v[240:243], v[0:3]
	s_setprio 0
	s_barrier
	s_add_u32 s0, s0, 0x100
	s_addc_u32 s1, s1, 0
	v_lshl_add_u64 v[130:131], v[130:131], 0, s[94:95]
	v_lshl_add_u64 v[128:129], v[128:129], 0, s[94:95]
	s_cmp_ge_u32 s57, s16
	s_mov_b32 s38, s57
	s_cbranch_scc0 .LBB0_318
	v_readlane_b32 s0, v254, 50
	v_readlane_b32 s1, v254, 51
	s_and_b64 vcc, exec, s[0:1]
	s_mov_b32 s68, 0x134000
	s_mov_b32 s69, 0x160000
	s_cbranch_vccz .LBB0_321
	s_barrier

; #define PG8_STAGE(bufoff, gbase, voff) do { _Pragma("unroll") for (int _i = 0; _i < 2; ++_i) \
;         __builtin_amdgcn_global_load_lds((const unsigned*)((const char*)(gbase) + (voff)[_i]), (LAS unsigned*)(lds + (bufoff) + ldsw + _i * 8192), 16, 0, 0); } while (0)
; #define PG8_LDA(dst, b, h) do { _Pragma("unroll") for (int m = 0; m < 4; ++m) _Pragma("unroll") for (int k = 0; k < 2; ++k) dst[m][k] = *(const LAS bf16x8*)(lds + PG8_SA(b, h) + aoff + m * 2048 + k * 1024); } while (0)
; #define PG8_LDB(dst, b, h) do { _Pragma("unroll") for (int n = 0; n < 2; ++n) _Pragma("unroll") for (int k = 0; k < 2; ++k) dst[n][k] = *(const LAS bf16x8*)(lds + PG8_SB(b, h) + boff + n * 2048 + k * 1024); } while (0)
; #define PG8_MMA(ai, bj, At, Bt) do { __builtin_amdgcn_s_setprio(1); _Pragma("unroll") for (int m = 0; m < 4; ++m) _Pragma("unroll") for (int n = 0; n < 2; ++n) _Pragma("unroll") for (int k = 0; k < 2; ++k) \
;         acc[ai][bj][m][n] = __builtin_amdgcn_mfma_f32_16x16x32_bf16(Bt[n][k], At[m][k], acc[ai][bj][m][n], 0, 0, 0); __builtin_amdgcn_s_setprio(0); } while (0)
; #define PG8_WAIT_V(n) asm volatile("s_waitcnt vmcnt(" #n ")" ::: "memory")
; #define PG8_WAIT_L(n) asm volatile("s_waitcnt lgkmcnt(" #n ")" ::: "memory")
; #define PG8_BAR __builtin_amdgcn_s_barrier()
; #define PG8_SCHED __builtin_amdgcn_sched_barrier(0)
;     ...
;         for (int t = 0; t < nt; t += 2) {
;             const bool last = (t == nt - 2);
;             const char* a1 = cA + (size_t)(t + 1) * kstep;
;             const char* a2 = last ? nA : cA + (size_t)(t + 2) * kstep; const char* b2 = last ? nB : cB + (size_t)(t + 2) * kstep;
;             const char* a3 = a2 + kstep; const char* b3 = b2 + kstep;
;             PG8_LDB(B0, 0, 0); PG8_LDB(B1, 0, 1); PG8_SCHED; PG8_LDA(At, 0, 0); PG8_STAGE(PG8_SA(1, 1), a1 + hstepA, voffA);
;             PG8_WAIT_V(8); PG8_WAIT_L(0); PG8_BAR; PG8_MMA(0, 0, At, B0); PG8_MMA(0, 1, At, B1); PG8_BAR; PG8_SCHED;
;             PG8_LDA(At, 0, 1); PG8_STAGE(PG8_SB(0, 0), b2, voffB); PG8_STAGE(PG8_SB(0, 1), b2 + hstepB, voffB); PG8_STAGE(PG8_SA(0, 0), a2, voffA);
;             PG8_WAIT_V(8); PG8_WAIT_L(0); PG8_BAR; PG8_MMA(1, 0, At, B0); PG8_MMA(1, 1, At, B1); PG8_BAR; PG8_SCHED;
.LBB0_416:
	s_add_i32 s8, s2, 2
	s_add_u32 s9, s52, s0
	s_addc_u32 s3, s53, s1
	s_add_i32 s26, 0, 0x10000
	s_cmp_eq_u32 s65, s2
	s_cselect_b32 s3, s6, s3
	s_cselect_b32 s2, s7, s9
	v_add_u32_e32 v153, s26, v148
	s_cselect_b64 vcc, -1, 0
	s_add_i32 s9, 0, 0x14000
	v_lshl_add_u64 v[170:171], v[128:129], 0, s[0:1]
	ds_read_b128 v[154:157], v153
	ds_read_b128 v[158:161], v153 offset:1024
	ds_read_b128 v[162:165], v153 offset:2048
	ds_read_b128 v[166:169], v153 offset:3072
	v_add_u32_e32 v153, s9, v148
	v_cndmask_b32_e32 v205, v171, v151, vcc
	v_cndmask_b32_e32 v204, v170, v152, vcc
	ds_read_b128 v[170:173], v153
	ds_read_b128 v[174:177], v153 offset:1024
	ds_read_b128 v[178:181], v153 offset:2048
	ds_read_b128 v[188:191], v153 offset:3072
	v_lshl_add_u64 v[244:245], s[52:53], 0, v[146:147]
	s_add_i32 m0, s41, 0xc000
	ds_read_b128 v[192:195], v149
	ds_read_b128 v[196:199], v149 offset:1024
	ds_read_b128 v[200:203], v149 offset:2048
	ds_read_b128 v[224:227], v149 offset:3072
	ds_read_b128 v[228:231], v149 offset:4096
	ds_read_b128 v[232:235], v149 offset:5120
	ds_read_b128 v[236:239], v149 offset:6144
	ds_read_b128 v[240:243], v149 offset:7168
	global_load_lds_dwordx4 v[244:245], off
	v_lshl_add_u64 v[244:245], s[52:53], 0, v[144:145]
	s_add_i32 m0, s41, 0xe000
	s_nop 0
	global_load_lds_dwordx4 v[244:245], off
	s_waitcnt vmcnt(8)
	s_waitcnt lgkmcnt(0)
	s_barrier
	s_setprio 1
	s_waitcnt lgkmcnt(0)
	v_mfma_f32_16x16x32_bf16 v[124:127], v[154:157], v[192:195], v[124:127]
	v_mfma_f32_16x16x32_bf16 v[120:123], v[162:165], v[192:195], v[120:123]
	v_mfma_f32_16x16x32_bf16 v[116:119], v[154:157], v[200:203], v[116:119]
	v_mfma_f32_16x16x32_bf16 v[112:115], v[162:165], v[200:203], v[112:115]
	v_mfma_f32_16x16x32_bf16 v[108:111], v[154:157], v[228:231], v[108:111]
	v_mfma_f32_16x16x32_bf16 v[104:107], v[162:165], v[228:231], v[104:107]
	v_lshl_add_u64 v[244:245], v[204:205], 0, v[132:133]
	v_mfma_f32_16x16x32_bf16 v[100:103], v[154:157], v[236:239], v[100:103]
	v_mfma_f32_16x16x32_bf16 v[96:99], v[162:165], v[236:239], v[96:99]
	v_lshl_add_u64 v[246:247], v[204:205], 0, v[136:137]
	v_mfma_f32_16x16x32_bf16 v[124:127], v[158:161], v[196:199], v[124:127]
	v_mfma_f32_16x16x32_bf16 v[120:123], v[166:169], v[196:199], v[120:123]
	v_lshl_add_u64 v[204:205], v[204:205], 0, s[58:59]
	v_mfma_f32_16x16x32_bf16 v[116:119], v[158:161], v[224:227], v[116:119]
	v_mfma_f32_16x16x32_bf16 v[112:115], v[166:169], v[224:227], v[112:115]
	v_lshl_add_u64 v[248:249], v[204:205], 0, v[132:133]
	v_mfma_f32_16x16x32_bf16 v[108:111], v[158:161], v[232:235], v[108:111]
	v_mfma_f32_16x16x32_bf16 v[104:107], v[166:169], v[232:235], v[104:107]
	v_lshl_add_u64 v[204:205], v[204:205], 0, v[136:137]
	v_mfma_f32_16x16x32_bf16 v[100:103], v[158:161], v[240:243], v[100:103]
	v_mfma_f32_16x16x32_bf16 v[96:99], v[166:169], v[240:243], v[96:99]
	v_lshl_add_u64 v[250:251], s[2:3], 0, v[130:131]
	v_mfma_f32_16x16x32_bf16 v[92:95], v[170:173], v[192:195], v[92:95]
	v_mfma_f32_16x16x32_bf16 v[88:91], v[178:181], v[192:195], v[88:91]
	v_lshl_add_u64 v[218:219], s[2:3], 0, v[134:135]
	v_mfma_f32_16x16x32_bf16 v[84:87], v[170:173], v[200:203], v[84:87]
	v_mfma_f32_16x16x32_bf16 v[80:83], v[178:181], v[200:203], v[80:83]
	v_mfma_f32_16x16x32_bf16 v[76:79], v[170:173], v[228:231], v[76:79]
	v_mfma_f32_16x16x32_bf16 v[72:75], v[178:181], v[228:231], v[72:75]
	v_mfma_f32_16x16x32_bf16 v[68:71], v[170:173], v[236:239], v[68:71]
	v_mfma_f32_16x16x32_bf16 v[64:67], v[178:181], v[236:239], v[64:67]
	v_mfma_f32_16x16x32_bf16 v[92:95], v[174:177], v[196:199], v[92:95]
	v_mfma_f32_16x16x32_bf16 v[88:91], v[188:191], v[196:199], v[88:91]
	v_mfma_f32_16x16x32_bf16 v[84:87], v[174:177], v[224:227], v[84:87]
	v_mfma_f32_16x16x32_bf16 v[80:83], v[188:191], v[224:227], v[80:83]
	v_mfma_f32_16x16x32_bf16 v[76:79], v[174:177], v[232:235], v[76:79]
	v_mfma_f32_16x16x32_bf16 v[72:75], v[188:191], v[232:235], v[72:75]
	v_mfma_f32_16x16x32_bf16 v[68:71], v[174:177], v[240:243], v[68:71]
	v_mfma_f32_16x16x32_bf16 v[64:67], v[188:191], v[240:243], v[64:67]
	s_setprio 0
	s_barrier
	s_add_i32 s26, s26, s40
	s_mov_b32 m0, s26
	ds_read_b128 v[192:195], v149 offset:16384
	ds_read_b128 v[196:199], v149 offset:17408
	ds_read_b128 v[200:203], v149 offset:18432
	ds_read_b128 v[224:227], v149 offset:19456
	ds_read_b128 v[228:231], v149 offset:20480
	ds_read_b128 v[232:235], v149 offset:21504
	ds_read_b128 v[236:239], v149 offset:22528
	ds_read_b128 v[240:243], v149 offset:23552
	global_load_lds_dwordx4 v[244:245], off
	s_add_i32 m0, s26, 0x2000
	s_add_i32 s9, s9, s40
	global_load_lds_dwordx4 v[246:247], off
	s_mov_b32 m0, s9
	s_nop 0
	global_load_lds_dwordx4 v[248:249], off
	s_add_i32 m0, s9, 0x2000
	s_nop 0
	global_load_lds_dwordx4 v[204:205], off
	s_mov_b32 m0, s41
	s_nop 0
	global_load_lds_dwordx4 v[250:251], off
	s_mov_b32 m0, s49
	s_nop 0
	global_load_lds_dwordx4 v[218:219], off
	s_waitcnt vmcnt(8)
	s_waitcnt lgkmcnt(0)
	s_barrier
; #define PG8_STAGE(bufoff, gbase, voff) do { _Pragma("unroll") for (int _i = 0; _i < 2; ++_i) \
;         __builtin_amdgcn_global_load_lds((const unsigned*)((const char*)(gbase) + (voff)[_i]), (LAS unsigned*)(lds + (bufoff) + ldsw + _i * 8192), 16, 0, 0); } while (0)
; #define PG8_LDA(dst, b, h) do { _Pragma("unroll") for (int m = 0; m < 4; ++m) _Pragma("unroll") for (int k = 0; k < 2; ++k) dst[m][k] = *(const LAS bf16x8*)(lds + PG8_SA(b, h) + aoff + m * 2048 + k * 1024); } while (0)
; #define PG8_LDB(dst, b, h) do { _Pragma("unroll") for (int n = 0; n < 2; ++n) _Pragma("unroll") for (int k = 0; k < 2; ++k) dst[n][k] = *(const LAS bf16x8*)(lds + PG8_SB(b, h) + boff + n * 2048 + k * 1024); } while (0)
; #define PG8_MMA(ai, bj, At, Bt) do { __builtin_amdgcn_s_setprio(1); _Pragma("unroll") for (int m = 0; m < 4; ++m) _Pragma("unroll") for (int n = 0; n < 2; ++n) _Pragma("unroll") for (int k = 0; k < 2; ++k) \
;         acc[ai][bj][m][n] = __builtin_amdgcn_mfma_f32_16x16x32_bf16(Bt[n][k], At[m][k], acc[ai][bj][m][n], 0, 0, 0); __builtin_amdgcn_s_setprio(0); } while (0)
; #define PG8_WAIT_V(n) asm volatile("s_waitcnt vmcnt(" #n ")" ::: "memory")
; #define PG8_WAIT_L(n) asm volatile("s_waitcnt lgkmcnt(" #n ")" ::: "memory")
; #define PG8_BAR __builtin_amdgcn_s_barrier()
; #define PG8_SCHED __builtin_amdgcn_sched_barrier(0)
;     ...
;             PG8_WAIT_V(8); PG8_WAIT_L(0); PG8_BAR; PG8_MMA(1, 0, At, B0); PG8_MMA(1, 1, At, B1); PG8_BAR; PG8_SCHED;
;             PG8_LDB(B0, 1, 0); PG8_LDB(B1, 1, 1); PG8_SCHED; PG8_LDA(At, 1, 0); PG8_STAGE(PG8_SA(0, 1), a2 + hstepA, voffA);
;             PG8_WAIT_V(8); PG8_WAIT_L(0); PG8_BAR; PG8_MMA(0, 0, At, B0); PG8_MMA(0, 1, At, B1); PG8_BAR; PG8_SCHED;
	s_setprio 1
	s_waitcnt lgkmcnt(0)
	v_mfma_f32_16x16x32_bf16 v[60:63], v[154:157], v[192:195], v[60:63]
	v_mfma_f32_16x16x32_bf16 v[56:59], v[162:165], v[192:195], v[56:59]
	v_mfma_f32_16x16x32_bf16 v[52:55], v[154:157], v[200:203], v[52:55]
	v_mfma_f32_16x16x32_bf16 v[48:51], v[162:165], v[200:203], v[48:51]
	v_mfma_f32_16x16x32_bf16 v[44:47], v[154:157], v[228:231], v[44:47]
	v_mfma_f32_16x16x32_bf16 v[40:43], v[162:165], v[228:231], v[40:43]
	v_mfma_f32_16x16x32_bf16 v[36:39], v[154:157], v[236:239], v[36:39]
	v_mfma_f32_16x16x32_bf16 v[32:35], v[162:165], v[236:239], v[32:35]
	v_mfma_f32_16x16x32_bf16 v[60:63], v[158:161], v[196:199], v[60:63]
	v_mfma_f32_16x16x32_bf16 v[56:59], v[166:169], v[196:199], v[56:59]
	v_mfma_f32_16x16x32_bf16 v[52:55], v[158:161], v[224:227], v[52:55]
	v_mfma_f32_16x16x32_bf16 v[48:51], v[166:169], v[224:227], v[48:51]
	v_mfma_f32_16x16x32_bf16 v[44:47], v[158:161], v[232:235], v[44:47]
	v_mfma_f32_16x16x32_bf16 v[40:43], v[166:169], v[232:235], v[40:43]
	v_mfma_f32_16x16x32_bf16 v[36:39], v[158:161], v[240:243], v[36:39]
	v_mfma_f32_16x16x32_bf16 v[32:35], v[166:169], v[240:243], v[32:35]
	v_mfma_f32_16x16x32_bf16 v[28:31], v[170:173], v[192:195], v[28:31]
	v_mfma_f32_16x16x32_bf16 v[24:27], v[178:181], v[192:195], v[24:27]
	v_mfma_f32_16x16x32_bf16 v[20:23], v[170:173], v[200:203], v[20:23]
	v_mfma_f32_16x16x32_bf16 v[16:19], v[178:181], v[200:203], v[16:19]
	v_mfma_f32_16x16x32_bf16 v[12:15], v[170:173], v[228:231], v[12:15]
	v_mfma_f32_16x16x32_bf16 v[8:11], v[178:181], v[228:231], v[8:11]
	v_mfma_f32_16x16x32_bf16 v[4:7], v[170:173], v[236:239], v[4:7]
	v_mfma_f32_16x16x32_bf16 v[0:3], v[178:181], v[236:239], v[0:3]
	v_mfma_f32_16x16x32_bf16 v[28:31], v[174:177], v[196:199], v[28:31]
	v_mfma_f32_16x16x32_bf16 v[24:27], v[188:191], v[196:199], v[24:27]
	v_mfma_f32_16x16x32_bf16 v[20:23], v[174:177], v[224:227], v[20:23]
	v_mfma_f32_16x16x32_bf16 v[16:19], v[188:191], v[224:227], v[16:19]
	v_mfma_f32_16x16x32_bf16 v[12:15], v[174:177], v[232:235], v[12:15]
	v_mfma_f32_16x16x32_bf16 v[8:11], v[188:191], v[232:235], v[8:11]
	v_mfma_f32_16x16x32_bf16 v[4:7], v[174:177], v[240:243], v[4:7]
	v_mfma_f32_16x16x32_bf16 v[0:3], v[188:191], v[240:243], v[0:3]
	s_setprio 0
	s_barrier
	s_add_i32 s9, 0, 0x18000
	v_add_u32_e32 v153, s9, v148
	s_add_i32 s26, 0, 0x1c000
	ds_read_b128 v[154:157], v153
	ds_read_b128 v[158:161], v153 offset:1024
	ds_read_b128 v[162:165], v153 offset:2048
	ds_read_b128 v[166:169], v153 offset:3072
	v_add_u32_e32 v153, s26, v148
	ds_read_b128 v[170:173], v153
	ds_read_b128 v[174:177], v153 offset:1024
	ds_read_b128 v[178:181], v153 offset:2048
	ds_read_b128 v[188:191], v153 offset:3072
	s_add_u32 s2, s2, s58
	s_addc_u32 s3, s3, 0
	s_mov_b32 m0, s10
	v_lshl_add_u64 v[212:213], s[2:3], 0, v[130:131]
	ds_read_b128 v[192:195], v149 offset:32768
	ds_read_b128 v[196:199], v149 offset:33792
	ds_read_b128 v[200:203], v149 offset:34816
	ds_read_b128 v[224:227], v149 offset:35840
	ds_read_b128 v[228:231], v149 offset:36864
	ds_read_b128 v[232:235], v149 offset:37888
	ds_read_b128 v[236:239], v149 offset:38912
	ds_read_b128 v[240:243], v149 offset:39936
	global_load_lds_dwordx4 v[212:213], off
	v_lshl_add_u64 v[212:213], s[2:3], 0, v[134:135]
	s_mov_b32 m0, s11
	s_nop 0
	global_load_lds_dwordx4 v[212:213], off
	s_waitcnt vmcnt(8)
	s_waitcnt lgkmcnt(0)
	s_barrier
	s_setprio 1
	s_waitcnt lgkmcnt(0)
	v_mfma_f32_16x16x32_bf16 v[124:127], v[154:157], v[192:195], v[124:127]
	v_mfma_f32_16x16x32_bf16 v[120:123], v[162:165], v[192:195], v[120:123]
	v_mfma_f32_16x16x32_bf16 v[116:119], v[154:157], v[200:203], v[116:119]
	v_mfma_f32_16x16x32_bf16 v[112:115], v[162:165], v[200:203], v[112:115]
	v_mfma_f32_16x16x32_bf16 v[108:111], v[154:157], v[228:231], v[108:111]
	v_mfma_f32_16x16x32_bf16 v[104:107], v[162:165], v[228:231], v[104:107]
	v_mfma_f32_16x16x32_bf16 v[100:103], v[154:157], v[236:239], v[100:103]
	v_mfma_f32_16x16x32_bf16 v[96:99], v[162:165], v[236:239], v[96:99]
	v_mfma_f32_16x16x32_bf16 v[124:127], v[158:161], v[196:199], v[124:127]
	v_mfma_f32_16x16x32_bf16 v[120:123], v[166:169], v[196:199], v[120:123]
	v_mfma_f32_16x16x32_bf16 v[116:119], v[158:161], v[224:227], v[116:119]
	v_mfma_f32_16x16x32_bf16 v[112:115], v[166:169], v[224:227], v[112:115]
	v_mfma_f32_16x16x32_bf16 v[108:111], v[158:161], v[232:235], v[108:111]
	v_mfma_f32_16x16x32_bf16 v[104:107], v[166:169], v[232:235], v[104:107]
	v_mfma_f32_16x16x32_bf16 v[100:103], v[158:161], v[240:243], v[100:103]
	v_mfma_f32_16x16x32_bf16 v[96:99], v[166:169], v[240:243], v[96:99]
	v_mfma_f32_16x16x32_bf16 v[92:95], v[170:173], v[192:195], v[92:95]
	v_mfma_f32_16x16x32_bf16 v[88:91], v[178:181], v[192:195], v[88:91]
	v_mfma_f32_16x16x32_bf16 v[84:87], v[170:173], v[200:203], v[84:87]
	v_mfma_f32_16x16x32_bf16 v[80:83], v[178:181], v[200:203], v[80:83]
	v_mfma_f32_16x16x32_bf16 v[76:79], v[170:173], v[228:231], v[76:79]
	v_mfma_f32_16x16x32_bf16 v[72:75], v[178:181], v[228:231], v[72:75]
	v_mfma_f32_16x16x32_bf16 v[68:71], v[170:173], v[236:239], v[68:71]
	v_mfma_f32_16x16x32_bf16 v[64:67], v[178:181], v[236:239], v[64:67]
	v_mfma_f32_16x16x32_bf16 v[92:95], v[174:177], v[196:199], v[92:95]
	v_mfma_f32_16x16x32_bf16 v[88:91], v[188:191], v[196:199], v[88:91]
	v_mfma_f32_16x16x32_bf16 v[84:87], v[174:177], v[224:227], v[84:87]
	v_mfma_f32_16x16x32_bf16 v[80:83], v[188:191], v[224:227], v[80:83]
	v_mfma_f32_16x16x32_bf16 v[76:79], v[174:177], v[232:235], v[76:79]
	v_mfma_f32_16x16x32_bf16 v[72:75], v[188:191], v[232:235], v[72:75]
	v_mfma_f32_16x16x32_bf16 v[68:71], v[174:177], v[240:243], v[68:71]
	v_mfma_f32_16x16x32_bf16 v[64:67], v[188:191], v[240:243], v[64:67]
	s_setprio 0
	s_barrier
; #define PG8_STAGE(bufoff, gbase, voff) do { _Pragma("unroll") for (int _i = 0; _i < 2; ++_i) \
;         __builtin_amdgcn_global_load_lds((const unsigned*)((const char*)(gbase) + (voff)[_i]), (LAS unsigned*)(lds + (bufoff) + ldsw + _i * 8192), 16, 0, 0); } while (0)
; #define PG8_LDA(dst, b, h) do { _Pragma("unroll") for (int m = 0; m < 4; ++m) _Pragma("unroll") for (int k = 0; k < 2; ++k) dst[m][k] = *(const LAS bf16x8*)(lds + PG8_SA(b, h) + aoff + m * 2048 + k * 1024); } while (0)
; #define PG8_MMA(ai, bj, At, Bt) do { __builtin_amdgcn_s_setprio(1); _Pragma("unroll") for (int m = 0; m < 4; ++m) _Pragma("unroll") for (int n = 0; n < 2; ++n) _Pragma("unroll") for (int k = 0; k < 2; ++k) \
;         acc[ai][bj][m][n] = __builtin_amdgcn_mfma_f32_16x16x32_bf16(Bt[n][k], At[m][k], acc[ai][bj][m][n], 0, 0, 0); __builtin_amdgcn_s_setprio(0); } while (0)
; #define PG8_WAIT_V(n) asm volatile("s_waitcnt vmcnt(" #n ")" ::: "memory")
; #define PG8_WAIT_L(n) asm volatile("s_waitcnt lgkmcnt(" #n ")" ::: "memory")
; #define PG8_BAR __builtin_amdgcn_s_barrier()
; #define PG8_SCHED __builtin_amdgcn_sched_barrier(0)
;     ...
;             PG8_LDA(At, 1, 1); PG8_STAGE(PG8_SB(1, 0), b3, voffB); PG8_STAGE(PG8_SB(1, 1), b3 + hstepB, voffB); PG8_STAGE(PG8_SA(1, 0), a3, voffA);
;             PG8_WAIT_V(8); PG8_WAIT_L(0); PG8_BAR; PG8_MMA(1, 0, At, B0); PG8_MMA(1, 1, At, B1); PG8_BAR; PG8_SCHED;
;         }
;         if (wr == 0) PG8_BAR;
	s_add_i32 s2, s9, s40
	s_add_i32 m0, s2, 0xffffff80
	ds_read_b128 v[192:195], v149 offset:49152
	ds_read_b128 v[196:199], v149 offset:50176
	ds_read_b128 v[200:203], v149 offset:51200
	ds_read_b128 v[224:227], v149 offset:52224
	ds_read_b128 v[228:231], v149 offset:53248
	ds_read_b128 v[232:235], v149 offset:54272
	ds_read_b128 v[236:239], v149 offset:55296
	ds_read_b128 v[240:243], v149 offset:56320
	global_load_lds_dwordx4 v[244:245], off offset:128
	s_add_i32 m0, s2, 0x1f80
	s_add_i32 s2, s26, s40
	global_load_lds_dwordx4 v[246:247], off offset:128
	s_add_i32 m0, s2, 0xffffff80
	s_nop 0
	global_load_lds_dwordx4 v[248:249], off offset:128
	s_add_i32 m0, s2, 0x1f80
	s_nop 0
	global_load_lds_dwordx4 v[204:205], off offset:128
	s_add_i32 m0, s51, 0xffffff80
	s_nop 0
	global_load_lds_dwordx4 v[250:251], off offset:128
	s_add_i32 m0, s64, 0xffffff80
	s_nop 0
	global_load_lds_dwordx4 v[218:219], off offset:128
	s_waitcnt vmcnt(8)
	s_waitcnt lgkmcnt(0)
	s_barrier
	s_setprio 1
	s_waitcnt lgkmcnt(0)
	v_mfma_f32_16x16x32_bf16 v[60:63], v[154:157], v[192:195], v[60:63]
	v_mfma_f32_16x16x32_bf16 v[56:59], v[162:165], v[192:195], v[56:59]
	v_mfma_f32_16x16x32_bf16 v[52:55], v[154:157], v[200:203], v[52:55]
	v_mfma_f32_16x16x32_bf16 v[48:51], v[162:165], v[200:203], v[48:51]
	v_mfma_f32_16x16x32_bf16 v[44:47], v[154:157], v[228:231], v[44:47]
	v_mfma_f32_16x16x32_bf16 v[40:43], v[162:165], v[228:231], v[40:43]
	v_mfma_f32_16x16x32_bf16 v[36:39], v[154:157], v[236:239], v[36:39]
	v_mfma_f32_16x16x32_bf16 v[32:35], v[162:165], v[236:239], v[32:35]
	v_mfma_f32_16x16x32_bf16 v[60:63], v[158:161], v[196:199], v[60:63]
	v_mfma_f32_16x16x32_bf16 v[56:59], v[166:169], v[196:199], v[56:59]
	v_mfma_f32_16x16x32_bf16 v[52:55], v[158:161], v[224:227], v[52:55]
	v_mfma_f32_16x16x32_bf16 v[48:51], v[166:169], v[224:227], v[48:51]
	v_mfma_f32_16x16x32_bf16 v[44:47], v[158:161], v[232:235], v[44:47]
	v_mfma_f32_16x16x32_bf16 v[40:43], v[166:169], v[232:235], v[40:43]
	v_mfma_f32_16x16x32_bf16 v[36:39], v[158:161], v[240:243], v[36:39]
	v_mfma_f32_16x16x32_bf16 v[32:35], v[166:169], v[240:243], v[32:35]
	v_mfma_f32_16x16x32_bf16 v[28:31], v[170:173], v[192:195], v[28:31]
	v_mfma_f32_16x16x32_bf16 v[24:27], v[178:181], v[192:195], v[24:27]
	v_mfma_f32_16x16x32_bf16 v[20:23], v[170:173], v[200:203], v[20:23]
	v_mfma_f32_16x16x32_bf16 v[16:19], v[178:181], v[200:203], v[16:19]
	v_mfma_f32_16x16x32_bf16 v[12:15], v[170:173], v[228:231], v[12:15]
	v_mfma_f32_16x16x32_bf16 v[8:11], v[178:181], v[228:231], v[8:11]
	v_mfma_f32_16x16x32_bf16 v[4:7], v[170:173], v[236:239], v[4:7]
	v_mfma_f32_16x16x32_bf16 v[0:3], v[178:181], v[236:239], v[0:3]
	v_mfma_f32_16x16x32_bf16 v[28:31], v[174:177], v[196:199], v[28:31]
	v_mfma_f32_16x16x32_bf16 v[24:27], v[188:191], v[196:199], v[24:27]
	v_mfma_f32_16x16x32_bf16 v[20:23], v[174:177], v[224:227], v[20:23]
	v_mfma_f32_16x16x32_bf16 v[16:19], v[188:191], v[224:227], v[16:19]
	v_mfma_f32_16x16x32_bf16 v[12:15], v[174:177], v[232:235], v[12:15]
	v_mfma_f32_16x16x32_bf16 v[8:11], v[188:191], v[232:235], v[8:11]
	v_mfma_f32_16x16x32_bf16 v[4:7], v[174:177], v[240:243], v[4:7]
	v_mfma_f32_16x16x32_bf16 v[0:3], v[188:191], v[240:243], v[0:3]
	s_setprio 0
	s_barrier
	s_add_u32 s0, s0, 0x100
	s_addc_u32 s1, s1, 0
	v_lshl_add_u64 v[146:147], v[146:147], 0, s[94:95]
	v_lshl_add_u64 v[144:145], v[144:145], 0, s[94:95]
	s_cmp_ge_u32 s8, s48
	s_mov_b32 s2, s8
	s_cbranch_scc0 .LBB0_416
	v_readlane_b32 s0, v254, 45
	v_readlane_b32 s1, v254, 46
	s_and_b64 vcc, exec, s[0:1]
	s_cbranch_vccz .LBB0_419
	s_barrier
